# in-proj GEMM epilogues: row statistics prefetched by LDS-DMA into wave-private spare LDS at unit start instead of a dependent global load at epilogue start
# speedup vs baseline: 1.0028x; 1.0028x over previous
.LBB0_211:
	s_ashr_i32 s31, s30, 31
	s_lshl_b64 s[8:9], s[30:31], 18
	s_add_u32 s44, s40, s8
	s_addc_u32 s45, s41, s9
	s_and_b64 s[8:9], s[66:67], exec
	s_cselect_b32 s31, s45, s11
	s_cselect_b32 s90, s44, s10
	s_ashr_i32 s35, s34, 31
	s_lshl_b64 s[8:9], s[34:35], 18
	s_add_u32 s14, s2, s8
	s_addc_u32 s15, s28, s9
	s_and_b64 s[8:9], s[66:67], exec
	s_cselect_b32 s35, s15, s73
	s_cselect_b32 s91, s14, s72
	s_add_u32 s10, s10, 0x20080
	s_addc_u32 s11, s11, 0
	s_add_u32 s92, s72, 0x100
	v_mov_b32_e32 v34, 0
	s_addc_u32 s93, s73, 0
	s_mov_b32 s94, -2
	v_lshrrev_b32_e32 v161, 6, v218
	s_nop 0
	v_readfirstlane_b32 s8, v161
	s_lshl_b32 s8, s8, 10
	s_add_i32 m0, s8, 0x20000
	s_lshl_b32 s8, s89, 10
	s_add_u32 s8, s12, s8
	s_addc_u32 s9, s13, 0
	v_and_b32_e32 v161, 0x100, v218
	v_and_b32_e32 v160, 63, v218
	v_lshl_or_b32 v160, v160, 2, v161
	global_load_lds_dword v160, s[8:9]
	global_load_lds_dword v160, s[8:9] offset:512
	v_mov_b32_e32 v35, v34
	v_mov_b32_e32 v36, v34
	v_mov_b32_e32 v37, v34
	v_mov_b32_e32 v38, v34
	v_mov_b32_e32 v39, v34
	v_mov_b32_e32 v40, v34
	v_mov_b32_e32 v41, v34
	v_mov_b32_e32 v50, v34
	v_mov_b32_e32 v51, v34
	v_mov_b32_e32 v52, v34
	v_mov_b32_e32 v53, v34
	v_mov_b32_e32 v54, v34
	v_mov_b32_e32 v55, v34
	v_mov_b32_e32 v56, v34
	v_mov_b32_e32 v57, v34
	v_mov_b32_e32 v66, v34
	v_mov_b32_e32 v67, v34
	v_mov_b32_e32 v68, v34
	v_mov_b32_e32 v69, v34
	v_mov_b32_e32 v70, v34
	v_mov_b32_e32 v71, v34
	v_mov_b32_e32 v72, v34
	v_mov_b32_e32 v73, v34
	v_mov_b32_e32 v82, v34
	v_mov_b32_e32 v83, v34
	v_mov_b32_e32 v84, v34
	v_mov_b32_e32 v85, v34
	v_mov_b32_e32 v86, v34
	v_mov_b32_e32 v87, v34
	v_mov_b32_e32 v88, v34
	v_mov_b32_e32 v89, v34
	v_mov_b32_e32 v42, v34
	v_mov_b32_e32 v43, v34
	v_mov_b32_e32 v44, v34
	v_mov_b32_e32 v45, v34
	v_mov_b32_e32 v46, v34
	v_mov_b32_e32 v47, v34
	v_mov_b32_e32 v48, v34
	v_mov_b32_e32 v49, v34
	v_mov_b32_e32 v58, v34
	v_mov_b32_e32 v59, v34
	v_mov_b32_e32 v60, v34
	v_mov_b32_e32 v61, v34
	v_mov_b32_e32 v62, v34
	v_mov_b32_e32 v63, v34
	v_mov_b32_e32 v64, v34
	v_mov_b32_e32 v65, v34
	v_mov_b32_e32 v74, v34
	v_mov_b32_e32 v75, v34
	v_mov_b32_e32 v76, v34
	v_mov_b32_e32 v77, v34
	v_mov_b32_e32 v78, v34
	v_mov_b32_e32 v79, v34
	v_mov_b32_e32 v80, v34
	v_mov_b32_e32 v81, v34
	v_mov_b32_e32 v90, v34
	v_mov_b32_e32 v91, v34
	v_mov_b32_e32 v92, v34
	v_mov_b32_e32 v93, v34
	v_mov_b32_e32 v94, v34
	v_mov_b32_e32 v95, v34
	v_mov_b32_e32 v96, v34
	v_mov_b32_e32 v97, v34
	v_mov_b32_e32 v98, v34
	v_mov_b32_e32 v99, v34
	v_mov_b32_e32 v100, v34
	v_mov_b32_e32 v101, v34
	v_mov_b32_e32 v102, v34
	v_mov_b32_e32 v103, v34
	v_mov_b32_e32 v104, v34
	v_mov_b32_e32 v105, v34
	v_mov_b32_e32 v114, v34
	v_mov_b32_e32 v115, v34
	v_mov_b32_e32 v116, v34
	v_mov_b32_e32 v117, v34
	v_mov_b32_e32 v118, v34
	v_mov_b32_e32 v119, v34
	v_mov_b32_e32 v120, v34
	v_mov_b32_e32 v121, v34
	v_mov_b32_e32 v130, v34
	v_mov_b32_e32 v131, v34
	v_mov_b32_e32 v132, v34
	v_mov_b32_e32 v133, v34
	v_mov_b32_e32 v134, v34
	v_mov_b32_e32 v135, v34
	v_mov_b32_e32 v136, v34
	v_mov_b32_e32 v137, v34
	v_mov_b32_e32 v146, v34
	v_mov_b32_e32 v147, v34
	v_mov_b32_e32 v148, v34
	v_mov_b32_e32 v149, v34
	v_mov_b32_e32 v150, v34
	v_mov_b32_e32 v151, v34
	v_mov_b32_e32 v152, v34
	v_mov_b32_e32 v153, v34
	v_mov_b32_e32 v106, v34
	v_mov_b32_e32 v107, v34
	v_mov_b32_e32 v108, v34
	v_mov_b32_e32 v109, v34
	v_mov_b32_e32 v110, v34
	v_mov_b32_e32 v111, v34
	v_mov_b32_e32 v112, v34
	v_mov_b32_e32 v113, v34
	v_mov_b32_e32 v122, v34
	v_mov_b32_e32 v123, v34
	v_mov_b32_e32 v124, v34
	v_mov_b32_e32 v125, v34
	v_mov_b32_e32 v126, v34
	v_mov_b32_e32 v127, v34
	v_mov_b32_e32 v128, v34
	v_mov_b32_e32 v129, v34
	v_mov_b32_e32 v138, v34
	v_mov_b32_e32 v139, v34
	v_mov_b32_e32 v140, v34
	v_mov_b32_e32 v141, v34
	v_mov_b32_e32 v142, v34
	v_mov_b32_e32 v143, v34
	v_mov_b32_e32 v144, v34
	v_mov_b32_e32 v145, v34
	v_mov_b32_e32 v154, v34
	v_mov_b32_e32 v155, v34
	v_mov_b32_e32 v156, v34
	v_mov_b32_e32 v157, v34
	v_mov_b32_e32 v158, v34
	v_mov_b32_e32 v159, v34
	v_mov_b32_e32 v160, v34
	v_mov_b32_e32 v161, v34

.LBB0_221:
	v_lshl_add_u32 v18, s89, 8, v207
	v_ashrrev_i32_e32 v19, 31, v18
	v_lshrrev_b32_e32 v2, 6, v218
	v_and_b32_e32 v3, 15, v218
	v_lshlrev_b32_e32 v3, 2, v3
	v_lshl_add_u32 v2, v2, 10, v3
	v_add_u32_e32 v2, 0x20000, v2
	ds_read_b32 v0, v2
	ds_read_b32 v31, v2 offset:64
	ds_read_b32 v30, v2 offset:128
	ds_read_b32 v29, v2 offset:192
	ds_read_b32 v28, v2 offset:512
	ds_read_b32 v27, v2 offset:576
	ds_read_b32 v26, v2 offset:640
	ds_read_b32 v19, v2 offset:704
	v_lshl_or_b32 v16, s88, 8, v209
	v_ashrrev_i32_e32 v17, 31, v16
	s_cmp_lt_i32 s31, 3
	s_waitcnt lgkmcnt(0)
	v_fmamk_f32 v0, v0, 0x3a800000, v219
	v_cmp_gt_f32_e32 vcc, s5, v0
	v_mul_f32_e32 v1, 0x4f800000, v0
	s_nop 0
	v_cndmask_b32_e32 v0, v0, v1, vcc
	v_sqrt_f32_e32 v1, v0
	s_nop 0
	v_add_u32_e32 v2, -1, v1
	v_fma_f32 v3, -v2, v1, v0
	v_cmp_ge_f32_e64 s[10:11], 0, v3
	v_add_u32_e32 v3, 1, v1
	s_nop 0
	v_cndmask_b32_e64 v2, v1, v2, s[10:11]
	v_fma_f32 v1, -v3, v1, v0
	v_cmp_lt_f32_e64 s[10:11], 0, v1
	s_nop 1
	v_cndmask_b32_e64 v1, v2, v3, s[10:11]
	v_mul_f32_e32 v2, 0x37800000, v1
	v_cndmask_b32_e32 v1, v1, v2, vcc
	v_cmp_class_f32_e32 vcc, v0, v220
	s_nop 1
	v_cndmask_b32_e32 v0, v1, v0, vcc
	v_div_scale_f32 v1, s[8:9], v0, v0, s81
	v_rcp_f32_e32 v2, v1
	s_nop 0
	v_fma_f32 v3, -v1, v2, 1.0
	v_fmac_f32_e32 v2, v3, v2
	v_div_scale_f32 v3, vcc, s81, v0, s81
	v_mul_f32_e32 v4, v3, v2
	v_fma_f32 v5, -v1, v4, v3
	v_fmac_f32_e32 v4, v5, v2
	v_fma_f32 v1, -v1, v4, v3
	v_div_fmas_f32 v1, v1, v2, v4
	v_div_fixup_f32 v22, v1, v0, s81
	v_mov_b64_e32 v[0:1], s[42:43]
	v_mad_i64_i32 v[20:21], s[8:9], v18, s70, v[0:1]
	v_pk_mul_f32 v[2:3], v[160:161], v[22:23] op_sel_hi:[1,0]
	v_pk_mul_f32 v[0:1], v[158:159], v[22:23] op_sel_hi:[1,0]
	v_pk_mul_f32 v[6:7], v[156:157], v[22:23] op_sel_hi:[1,0]
	v_pk_mul_f32 v[4:5], v[154:155], v[22:23] op_sel_hi:[1,0]
	s_cbranch_scc1 .LBB0_224
	s_cmp_gt_i32 s31, 3
	s_cbranch_scc0 .LBB0_225
	v_pk_mul_f32 v[10:11], v[2:3], s[78:79] op_sel_hi:[1,0]
	v_pk_mul_f32 v[8:9], v[0:1], s[78:79] op_sel_hi:[1,0]
	v_pk_mul_f32 v[14:15], v[6:7], s[78:79] op_sel_hi:[1,0]
	v_pk_mul_f32 v[12:13], v[4:5], s[78:79] op_sel_hi:[1,0]
	s_mov_b64 s[10:11], -1
	s_cbranch_execz .LBB0_226
	s_branch .LBB0_227

.LBB0_651:
	s_ashr_i32 s19, s18, 31
	s_lshl_b64 s[8:9], s[18:19], 19
	s_add_u32 s34, s36, s8
	s_addc_u32 s35, s37, s9
	s_and_b64 s[8:9], s[30:31], exec
	s_cselect_b32 s19, s35, s11
	s_cselect_b32 s89, s34, s10
	s_ashr_i32 s21, s20, 31
	s_lshl_b64 s[8:9], s[20:21], 19
	s_add_u32 s44, s2, s8
	s_addc_u32 s45, s28, s9
	s_and_b64 s[8:9], s[30:31], exec
	s_cselect_b32 s21, s45, s67
	s_cselect_b32 s90, s44, s66
	s_add_u32 s10, s10, 0x40080
	s_addc_u32 s11, s11, 0
	s_add_u32 s91, s66, 0x100
	v_mov_b32_e32 v0, 0
	s_addc_u32 s92, s67, 0
	s_mov_b32 s93, -2
	v_lshrrev_b32_e32 v129, 6, v218
	s_nop 0
	v_readfirstlane_b32 s8, v129
	s_lshl_b32 s8, s8, 10
	s_add_i32 m0, s8, 0x20000
	s_lshl_b32 s8, s88, 10
	s_add_u32 s8, s12, s8
	s_addc_u32 s9, s13, 0
	v_and_b32_e32 v129, 0x100, v218
	v_and_b32_e32 v128, 63, v218
	v_lshl_or_b32 v128, v128, 2, v129
	global_load_lds_dword v128, s[8:9]
	global_load_lds_dword v128, s[8:9] offset:512
	v_mov_b32_e32 v1, v0
	v_mov_b32_e32 v2, v0
	v_mov_b32_e32 v3, v0
	v_mov_b32_e32 v4, v0
	v_mov_b32_e32 v5, v0
	v_mov_b32_e32 v6, v0
	v_mov_b32_e32 v7, v0
	v_mov_b32_e32 v16, v0
	v_mov_b32_e32 v17, v0
	v_mov_b32_e32 v18, v0
	v_mov_b32_e32 v19, v0
	v_mov_b32_e32 v20, v0
	v_mov_b32_e32 v21, v0
	v_mov_b32_e32 v22, v0
	v_mov_b32_e32 v23, v0
	v_mov_b32_e32 v34, v0
	v_mov_b32_e32 v35, v0
	v_mov_b32_e32 v36, v0
	v_mov_b32_e32 v37, v0
	v_mov_b32_e32 v38, v0
	v_mov_b32_e32 v39, v0
	v_mov_b32_e32 v40, v0
	v_mov_b32_e32 v41, v0
	v_mov_b32_e32 v50, v0
	v_mov_b32_e32 v51, v0
	v_mov_b32_e32 v52, v0
	v_mov_b32_e32 v53, v0
	v_mov_b32_e32 v54, v0
	v_mov_b32_e32 v55, v0
	v_mov_b32_e32 v56, v0
	v_mov_b32_e32 v57, v0
	v_mov_b32_e32 v8, v0
	v_mov_b32_e32 v9, v0
	v_mov_b32_e32 v10, v0
	v_mov_b32_e32 v11, v0
	v_mov_b32_e32 v12, v0
	v_mov_b32_e32 v13, v0
	v_mov_b32_e32 v14, v0
	v_mov_b32_e32 v15, v0
	v_mov_b32_e32 v24, v0
	v_mov_b32_e32 v25, v0
	v_mov_b32_e32 v26, v0
	v_mov_b32_e32 v27, v0
	v_mov_b32_e32 v28, v0
	v_mov_b32_e32 v29, v0
	v_mov_b32_e32 v30, v0
	v_mov_b32_e32 v31, v0
	v_mov_b32_e32 v42, v0
	v_mov_b32_e32 v43, v0
	v_mov_b32_e32 v44, v0
	v_mov_b32_e32 v45, v0
	v_mov_b32_e32 v46, v0
	v_mov_b32_e32 v47, v0
	v_mov_b32_e32 v48, v0
	v_mov_b32_e32 v49, v0
	v_mov_b32_e32 v58, v0
	v_mov_b32_e32 v59, v0
	v_mov_b32_e32 v60, v0
	v_mov_b32_e32 v61, v0
	v_mov_b32_e32 v62, v0
	v_mov_b32_e32 v63, v0
	v_mov_b32_e32 v64, v0
	v_mov_b32_e32 v65, v0
	v_mov_b32_e32 v66, v0
	v_mov_b32_e32 v67, v0
	v_mov_b32_e32 v68, v0
	v_mov_b32_e32 v69, v0
	v_mov_b32_e32 v70, v0
	v_mov_b32_e32 v71, v0
	v_mov_b32_e32 v72, v0
	v_mov_b32_e32 v73, v0
	v_mov_b32_e32 v82, v0
	v_mov_b32_e32 v83, v0
	v_mov_b32_e32 v84, v0
	v_mov_b32_e32 v85, v0
	v_mov_b32_e32 v86, v0
	v_mov_b32_e32 v87, v0
	v_mov_b32_e32 v88, v0
	v_mov_b32_e32 v89, v0
	v_mov_b32_e32 v98, v0
	v_mov_b32_e32 v99, v0
	v_mov_b32_e32 v100, v0
	v_mov_b32_e32 v101, v0
	v_mov_b32_e32 v102, v0
	v_mov_b32_e32 v103, v0
	v_mov_b32_e32 v104, v0
	v_mov_b32_e32 v105, v0
	v_mov_b32_e32 v114, v0
	v_mov_b32_e32 v115, v0
	v_mov_b32_e32 v116, v0
	v_mov_b32_e32 v117, v0
	v_mov_b32_e32 v118, v0
	v_mov_b32_e32 v119, v0
	v_mov_b32_e32 v120, v0
	v_mov_b32_e32 v121, v0
	v_mov_b32_e32 v74, v0
	v_mov_b32_e32 v75, v0
	v_mov_b32_e32 v76, v0
	v_mov_b32_e32 v77, v0
	v_mov_b32_e32 v78, v0
	v_mov_b32_e32 v79, v0
	v_mov_b32_e32 v80, v0
	v_mov_b32_e32 v81, v0
	v_mov_b32_e32 v90, v0
	v_mov_b32_e32 v91, v0
	v_mov_b32_e32 v92, v0
	v_mov_b32_e32 v93, v0
	v_mov_b32_e32 v94, v0
	v_mov_b32_e32 v95, v0
	v_mov_b32_e32 v96, v0
	v_mov_b32_e32 v97, v0
	v_mov_b32_e32 v106, v0
	v_mov_b32_e32 v107, v0
	v_mov_b32_e32 v108, v0
	v_mov_b32_e32 v109, v0
	v_mov_b32_e32 v110, v0
	v_mov_b32_e32 v111, v0
	v_mov_b32_e32 v112, v0
	v_mov_b32_e32 v113, v0
	v_mov_b32_e32 v122, v0
	v_mov_b32_e32 v123, v0
	v_mov_b32_e32 v124, v0
	v_mov_b32_e32 v125, v0
	v_mov_b32_e32 v126, v0
	v_mov_b32_e32 v127, v0
	v_mov_b32_e32 v128, v0
	v_mov_b32_e32 v129, v0

.LBB0_661:
	v_lshl_add_u32 v150, s88, 8, v158
	v_ashrrev_i32_e32 v151, 31, v150
	v_lshrrev_b32_e32 v132, 6, v218
	v_and_b32_e32 v133, 15, v218
	v_lshlrev_b32_e32 v133, 2, v133
	v_lshl_add_u32 v132, v132, 10, v133
	v_add_u32_e32 v132, 0x20000, v132
	ds_read_b32 v130, v132
	ds_read_b32 v167, v132 offset:64
	ds_read_b32 v166, v132 offset:128
	ds_read_b32 v165, v132 offset:192
	ds_read_b32 v164, v132 offset:512
	ds_read_b32 v163, v132 offset:576
	ds_read_b32 v162, v132 offset:640
	ds_read_b32 v151, v132 offset:704
	v_lshl_or_b32 v148, s87, 8, v160
	v_ashrrev_i32_e32 v149, 31, v148
	s_cmp_lt_i32 s19, 3
	s_mov_b32 s73, 0x3b000000
	s_waitcnt lgkmcnt(0)
	v_fmamk_f32 v130, v130, 0x3a800000, v219
	v_cmp_gt_f32_e32 vcc, s5, v130
	v_mul_f32_e32 v131, 0x4f800000, v130
	s_nop 0
	v_cndmask_b32_e32 v130, v130, v131, vcc
	v_sqrt_f32_e32 v131, v130
	s_nop 0
	v_add_u32_e32 v132, -1, v131
	v_fma_f32 v133, -v132, v131, v130
	v_cmp_ge_f32_e64 s[10:11], 0, v133
	v_add_u32_e32 v133, 1, v131
	s_nop 0
	v_cndmask_b32_e64 v132, v131, v132, s[10:11]
	v_fma_f32 v131, -v133, v131, v130
	v_cmp_lt_f32_e64 s[10:11], 0, v131
	s_nop 1
	v_cndmask_b32_e64 v131, v132, v133, s[10:11]
	v_mul_f32_e32 v132, 0x37800000, v131
	v_cndmask_b32_e32 v131, v131, v132, vcc
	v_cmp_class_f32_e32 vcc, v130, v220
	s_nop 1
	v_cndmask_b32_e32 v130, v131, v130, vcc
	v_div_scale_f32 v131, s[8:9], v130, v130, 1.0
	v_rcp_f32_e32 v132, v131
	s_nop 0
	v_fma_f32 v133, -v131, v132, 1.0
	v_fmac_f32_e32 v132, v133, v132
	v_div_scale_f32 v133, vcc, 1.0, v130, 1.0
	v_mul_f32_e32 v134, v133, v132
	v_fma_f32 v135, -v131, v134, v133
	v_fmac_f32_e32 v134, v135, v132
	v_fma_f32 v131, -v131, v134, v133
	v_div_fmas_f32 v131, v131, v132, v134
	v_div_fixup_f32 v154, v131, v130, 1.0
	v_mov_b64_e32 v[130:131], s[42:43]
	v_mad_i64_i32 v[152:153], s[8:9], v150, s70, v[130:131]
	v_pk_mul_f32 v[128:129], v[128:129], v[154:155] op_sel_hi:[1,0]
	v_pk_mul_f32 v[126:127], v[126:127], v[154:155] op_sel_hi:[1,0]
	v_pk_mul_f32 v[124:125], v[124:125], v[154:155] op_sel_hi:[1,0]
	v_pk_mul_f32 v[122:123], v[122:123], v[154:155] op_sel_hi:[1,0]
	s_cbranch_scc1 .LBB0_664
	s_cmp_gt_i32 s19, 3
	s_cbranch_scc0 .LBB0_665
	v_pk_mul_f32 v[132:133], v[128:129], s[78:79] op_sel_hi:[1,0]
	v_pk_mul_f32 v[130:131], v[126:127], s[78:79] op_sel_hi:[1,0]
	v_pk_mul_f32 v[136:137], v[124:125], s[78:79] op_sel_hi:[1,0]
	v_pk_mul_f32 v[134:135], v[122:123], s[78:79] op_sel_hi:[1,0]
	s_mov_b64 s[10:11], -1
	s_cbranch_execz .LBB0_666
	s_branch .LBB0_667
